# sample attention: next tile's first-half loads issued one by one between the score-phase MFMA groups; their bf16 conversion moved to the end of the tile
# speedup vs baseline: 1.0021x; 1.0000x over previous
; __device__ __forceinline__ int lau_v(int x) { asm volatile("" : "+v"(x)); return x; }
; #define AS_CV1(j_) do { if ((j_) < PAST / 64) { _Pragma("unroll") for (int i_ = 0; i_ < N1; ++i_) cv[i_] = AS_CVL(r1a[i_], r1b[i_]); } \
;     else { _Pragma("unroll") for (int i_ = 0; i_ < N1; ++i_) cv[i_] = AS_BC(r1a[i_]); } } while (0)
; #define AS_SLD(set, g_) do { _Pragma("unroll") for (int i_ = 0; i_ < 2; ++i_) { const int s_ = 2 * (g_) + i_; const int xs_ = (64 * (s_ & 3)) ^ xsl; \
;         fa[set][i_] = *(const bf16x8*)(lds + kb0 + xs_ + (s_ >> 2) * 16384); fb0[set][i_] = *(const bf16x8*)(lds + qb0 + xs_ + (s_ >> 2) * 16384); fb1[set][i_] = *(const bf16x8*)(lds + qb0 + xs_ + (s_ >> 2) * 16384 + 4096); } } while (0)
; __device__ __forceinline__ void unit(const bf16_t* __restrict__ Qs_bh  , const float* __restrict__ Clat  , const float* __restrict__ Ckpe  , const bf16_t* __restrict__ Kn  , ...
;     ...
;     if (j + 1 < NT) AS_LD1(j + 1);
;     f32x4 sa[2] = {{0.f, 0.f, 0.f, 0.f}, {0.f, 0.f, 0.f, 0.f}};
;     const int xsl = lau_v(xsh);
;     bf16x8 fa[2][2], fb0[2][2], fb1[2][2], fp[2];
;     ...
;     AS_SLD(0, 0);
; #pragma unroll
;     for (int g = 0; g < 8; ++g) {
;       if (g < 7) AS_SLD((g + 1) & 1, g + 1); else { fp[0] = *(const bf16x8*)(lds + kpb[0]); fp[1] = *(const bf16x8*)(lds + kpb[1]); }
;       __builtin_amdgcn_sched_barrier(0);
; #pragma unroll
;       for (int i = 0; i < 2; ++i) {
;         sa[0] = __builtin_amdgcn_mfma_f32_16x16x32_bf16(fa[g & 1][i], fb0[g & 1][i], sa[0], 0, 0, 0);
;         sa[1] = __builtin_amdgcn_mfma_f32_16x16x32_bf16(fa[g & 1][i], fb1[g & 1][i], sa[1], 0, 0, 0); }
;       __builtin_amdgcn_sched_barrier(0);
;     }
;     ...
; #pragma unroll
;     for (int s = 0; s < 2; ++s) {
;       sa[0] = __builtin_amdgcn_mfma_f32_16x16x32_bf16(fp[s], qpe[0][s], sa[0], 0, 0, 0);
;       sa[1] = __builtin_amdgcn_mfma_f32_16x16x32_bf16(fp[s], qpe[1][s], sa[1], 0, 0, 0); }
;     *(f32x4*)(lds + sxw) = sa[0]; *(f32x4*)(lds + sxw + 16 * SXLD) = sa[1];
;     __syncthreads();
;     if (j + 1 < NT) { AS_CV1(j + 1); AS_LD2(j + 1); }
.LBB0_1558:
	s_add_u32 s100, s47, s14
	s_addc_u32 s101, s48, s15
	s_add_u32 s100, s100, 0x20000
	s_addc_u32 s101, s101, 0
	v_lshlrev_b32_e32 v165, 5, v210
	v_mov_b32_e32 v0, v218
	s_nop 0
	v_add_u32_e32 v14, v219, v0
	v_add_u32_e32 v15, v220, v0
	v_xor_b32_e32 v188, 64, v0
	v_xor_b32_e32 v196, 0x80, v0
	v_xor_b32_e32 v0, 0xc0, v0
	v_add_u32_e32 v225, v220, v188
	v_add_u32_e32 v238, v219, v196
	v_add_u32_e32 v239, v220, v196
	v_add_u32_e32 v240, v219, v0
	v_add_u32_e32 v0, v220, v0
	ds_read_b128 v[2:5], v14
	ds_read_b128 v[6:9], v15
	v_add_u32_e32 v224, v219, v188
	ds_read_b128 v[10:13], v15 offset:4096
	ds_read_b128 v[184:187], v224
	ds_read_b128 v[188:191], v225
	ds_read_b128 v[192:195], v225 offset:4096
	ds_read_b128 v[196:199], v238
	ds_read_b128 v[200:203], v239
	ds_read_b128 v[226:229], v239 offset:4096
	ds_read_b128 v[230:233], v240
	ds_read_b128 v[234:237], v0
	ds_read_b128 v[242:245], v0 offset:4096
	s_waitcnt lgkmcnt(10)
	v_mfma_f32_16x16x32_bf16 v[6:9], v[2:5], v[6:9], 0
	s_waitcnt lgkmcnt(9)
	v_mfma_f32_16x16x32_bf16 v[2:5], v[2:5], v[10:13], 0
	s_waitcnt lgkmcnt(7)
	v_mfma_f32_16x16x32_bf16 v[6:9], v[184:187], v[188:191], v[6:9]
	s_waitcnt lgkmcnt(6)
	v_mfma_f32_16x16x32_bf16 v[2:5], v[184:187], v[192:195], v[2:5]
	s_cmp_lt_u32 s46, 63
	s_cbranch_scc0 .Lsa_sp0
	v_mov_b32_e32 v164, v165
	global_load_dwordx4 v[100:103], v164, s[100:101]
.Lsa_sp0:
	ds_read_b128 v[10:13], v14 offset:16384
	ds_read_b128 v[184:187], v15 offset:16384
	ds_read_b128 v[188:191], v15 offset:20480
	ds_read_b128 v[192:195], v224 offset:16384
	ds_read_b128 v[246:249], v225 offset:16384
	ds_read_b128 v[204:207], v225 offset:20480
	s_waitcnt lgkmcnt(10)
	v_mfma_f32_16x16x32_bf16 v[6:9], v[196:199], v[200:203], v[6:9]
	s_waitcnt lgkmcnt(9)
	v_mfma_f32_16x16x32_bf16 v[2:5], v[196:199], v[226:229], v[2:5]
	s_waitcnt lgkmcnt(7)
	v_mfma_f32_16x16x32_bf16 v[6:9], v[230:233], v[234:237], v[6:9]
	s_waitcnt lgkmcnt(6)
	v_mfma_f32_16x16x32_bf16 v[2:5], v[230:233], v[242:245], v[2:5]
	s_cmp_lt_u32 s46, 63
	s_cbranch_scc0 .Lsa_sp1
	global_load_dwordx4 v[96:99], v164, s[100:101] offset:16
.Lsa_sp1:
	ds_read_b128 v[196:199], v238 offset:16384
	ds_read_b128 v[200:203], v239 offset:16384
	ds_read_b128 v[226:229], v239 offset:20480
	ds_read_b128 v[230:233], v240 offset:16384
	ds_read_b128 v[234:237], v0 offset:16384
	ds_read_b128 v[242:245], v0 offset:20480
	s_waitcnt lgkmcnt(10)
	v_mfma_f32_16x16x32_bf16 v[6:9], v[10:13], v[184:187], v[6:9]
	s_waitcnt lgkmcnt(9)
	v_mfma_f32_16x16x32_bf16 v[2:5], v[10:13], v[188:191], v[2:5]
	s_waitcnt lgkmcnt(7)
	v_mfma_f32_16x16x32_bf16 v[6:9], v[192:195], v[246:249], v[6:9]
	s_waitcnt lgkmcnt(6)
	v_mfma_f32_16x16x32_bf16 v[2:5], v[192:195], v[204:207], v[2:5]
	s_cmp_lt_u32 s46, 63
	s_cbranch_scc0 .Lsa_sp2
	v_add_u32_e32 v164, 0x4000, v165
	global_load_dwordx4 v[112:115], v164, s[100:101]
.Lsa_sp2:
	ds_read_b128 v[10:13], v14 offset:32768
	ds_read_b128 v[184:187], v15 offset:32768
	ds_read_b128 v[188:191], v15 offset:36864
	ds_read_b128 v[192:195], v224 offset:32768
	ds_read_b128 v[204:207], v225 offset:32768
	ds_read_b128 v[246:249], v225 offset:36864
	s_waitcnt lgkmcnt(10)
	v_mfma_f32_16x16x32_bf16 v[6:9], v[196:199], v[200:203], v[6:9]
	s_waitcnt lgkmcnt(9)
	v_mfma_f32_16x16x32_bf16 v[2:5], v[196:199], v[226:229], v[2:5]
	s_waitcnt lgkmcnt(7)
	v_mfma_f32_16x16x32_bf16 v[6:9], v[230:233], v[234:237], v[6:9]
	s_waitcnt lgkmcnt(6)
	v_mfma_f32_16x16x32_bf16 v[2:5], v[230:233], v[242:245], v[2:5]
	s_cmp_lt_u32 s46, 63
	s_cbranch_scc0 .Lsa_sp3
	global_load_dwordx4 v[108:111], v164, s[100:101] offset:16
.Lsa_sp3:
	ds_read_b128 v[196:199], v238 offset:32768
	ds_read_b128 v[200:203], v239 offset:32768
	ds_read_b128 v[226:229], v239 offset:36864
	ds_read_b128 v[230:233], v240 offset:32768
	ds_read_b128 v[234:237], v0 offset:32768
	ds_read_b128 v[242:245], v0 offset:36864
	s_waitcnt lgkmcnt(10)
	v_mfma_f32_16x16x32_bf16 v[6:9], v[10:13], v[184:187], v[6:9]
	s_waitcnt lgkmcnt(9)
	v_mfma_f32_16x16x32_bf16 v[2:5], v[10:13], v[188:191], v[2:5]
	s_waitcnt lgkmcnt(7)
	v_mfma_f32_16x16x32_bf16 v[6:9], v[192:195], v[204:207], v[6:9]
	s_waitcnt lgkmcnt(6)
	v_mfma_f32_16x16x32_bf16 v[2:5], v[192:195], v[246:249], v[2:5]
	s_cmp_lt_u32 s46, 63
	s_cbranch_scc0 .Lsa_sp4
	v_add_u32_e32 v164, 0x8000, v165
	global_load_dwordx4 v[140:143], v164, s[100:101]
.Lsa_sp4:
	ds_read_b128 v[10:13], v14 offset:49152
	ds_read_b128 v[184:187], v15 offset:49152
	ds_read_b128 v[188:191], v15 offset:53248
	ds_read_b128 v[192:195], v224 offset:49152
	ds_read_b128 v[204:207], v225 offset:49152
	ds_read_b128 v[246:249], v225 offset:53248
	s_waitcnt lgkmcnt(10)
	v_mfma_f32_16x16x32_bf16 v[6:9], v[196:199], v[200:203], v[6:9]
	s_waitcnt lgkmcnt(9)
	v_mfma_f32_16x16x32_bf16 v[2:5], v[196:199], v[226:229], v[2:5]
	s_waitcnt lgkmcnt(7)
	v_mfma_f32_16x16x32_bf16 v[6:9], v[230:233], v[234:237], v[6:9]
	s_waitcnt lgkmcnt(6)
	v_mfma_f32_16x16x32_bf16 v[2:5], v[230:233], v[242:245], v[2:5]
	s_cmp_lt_u32 s46, 63
	s_cbranch_scc0 .Lsa_sp5
	global_load_dwordx4 v[120:123], v164, s[100:101] offset:16
.Lsa_sp5:
	ds_read_b128 v[196:199], v238 offset:49152
	ds_read_b128 v[200:203], v239 offset:49152
	ds_read_b128 v[226:229], v239 offset:53248
	ds_read_b128 v[230:233], v240 offset:49152
	ds_read_b128 v[234:237], v0 offset:49152
	ds_read_b128 v[242:245], v0 offset:53248
	s_waitcnt lgkmcnt(10)
	v_mfma_f32_16x16x32_bf16 v[6:9], v[10:13], v[184:187], v[6:9]
	s_waitcnt lgkmcnt(9)
	v_mfma_f32_16x16x32_bf16 v[2:5], v[10:13], v[188:191], v[2:5]
	s_waitcnt lgkmcnt(7)
	v_mfma_f32_16x16x32_bf16 v[6:9], v[192:195], v[204:207], v[6:9]
	s_waitcnt lgkmcnt(6)
	v_mfma_f32_16x16x32_bf16 v[2:5], v[192:195], v[246:249], v[2:5]
	s_cmp_lt_u32 s46, 63
	s_cbranch_scc0 .Lsa_sp6
	v_add_u32_e32 v164, 0xc000, v165
	global_load_dwordx4 v[152:155], v164, s[100:101]
.Lsa_sp6:
	ds_read_b128 v[10:13], v221
	ds_read_b128 v[184:187], v222
	s_waitcnt lgkmcnt(6)
	v_mfma_f32_16x16x32_bf16 v[6:9], v[196:199], v[200:203], v[6:9]
	s_waitcnt lgkmcnt(5)
	v_mfma_f32_16x16x32_bf16 v[2:5], v[196:199], v[226:229], v[2:5]
	s_waitcnt lgkmcnt(3)
	v_mfma_f32_16x16x32_bf16 v[6:9], v[230:233], v[234:237], v[6:9]
	s_waitcnt lgkmcnt(2)
	v_mfma_f32_16x16x32_bf16 v[2:5], v[230:233], v[242:245], v[2:5]
	s_cmp_lt_u32 s46, 63
	s_cbranch_scc0 .Lsa_sp7
	global_load_dwordx4 v[132:135], v164, s[100:101] offset:16
.Lsa_sp7:
	s_waitcnt lgkmcnt(0)
	v_mfma_f32_16x16x32_bf16 v[6:9], v[184:187], v[80:83], v[6:9]
	s_and_b64 vcc, exec, s[6:7]
	v_mfma_f32_16x16x32_bf16 v[2:5], v[184:187], v[88:91], v[2:5]
	v_mfma_f32_16x16x32_bf16 v[6:9], v[10:13], v[84:87], v[6:9]
	v_mfma_f32_16x16x32_bf16 v[2:5], v[10:13], v[92:95], v[2:5]
	s_nop 6
	ds_write_b128 v214, v[6:9]
	ds_write_b128 v214, v[2:5] offset:4352
	s_waitcnt lgkmcnt(0)
	s_barrier
	s_cbranch_vccnz .LBB0_1565
	s_cmp_gt_u32 s46, 62
	s_cselect_b64 s[6:7], -1, 0

; __device__ __forceinline__ unsigned cvt_pk_bf16(float lo, float hi) { const f32x2 v = {lo, hi}; unsigned r = __builtin_bit_cast(unsigned, __builtin_convertvector(v, bf16x2_t)); asm volatile("" : "+v"(r)); return r; }
; __device__ __forceinline__ int lau_v(int x) { asm volatile("" : "+v"(x)); return x; }
; template <int OFF> __device__ __forceinline__ s16x4 tr_read(int vb) { s16x4 r; asm volatile("ds_read_b64_tr_b16 %0, %1 offset:%2" : "=&v"(r) : "v"(vb), "i"(OFF) : "memory"); return r; }
; template <int OFF> __device__ __forceinline__ s16x4 tr_read(int a) { s16x4 r; asm volatile("ds_read_b64_tr_b16 %0, %1 offset:%2" : "=&v"(r) : "v"(a), "i"(OFF) : "memory"); return r; }
; __device__ __forceinline__ void unit(const bf16_t* __restrict__ Qs_bh  , const float* __restrict__ Clat  , const float* __restrict__ Ckpe  , const bf16_t* __restrict__ Kn  , ...
;     ...
;     bf16x8 pa[4];
; #pragma unroll
;     for (int ks = 0; ks < 4; ++ks) { u32x4 w; w.x = cvt_pk_bf16(sv[ks][0], sv[ks][1]); w.y = cvt_pk_bf16(sv[ks][2], sv[ks][3]); w.z = cvt_pk_bf16(sv[ks][4], sv[ks][5]); w.w = cvt_pk_bf16(sv[ks][6], sv[ks][7]); pa[ks] = *reinterpret_cast<bf16x8*>(&w); }
; #pragma unroll
;     for (int d0 = 0; d0 < 4; ++d0) {
;       const int xd = (64 * d0) ^ lau_v(q4s), va0 = vb[0] + xd, va1 = vb[1] + xd;
;       const s16x4 l0 = tr_read<0>(va0), h0 = tr_read<0>(va1), l1 = tr_read<4096>(va0), h1 = tr_read<4096>(va1);
;       const s16x4 l2 = tr_read<8192>(va0), h2 = tr_read<8192>(va1), l3 = tr_read<12288>(va0), h3 = tr_read<12288>(va1);
;       asm volatile("s_waitcnt lgkmcnt(0)" ::: "memory"); __builtin_amdgcn_sched_barrier(0);
;     ...
;       o[d0] = __builtin_amdgcn_mfma_f32_32x32x16_bf16(pa[0], AS_PK(l0, h0), o[d0], 0, 0, 0);
;       o[d0] = __builtin_amdgcn_mfma_f32_32x32x16_bf16(pa[1], AS_PK(l1, h1), o[d0], 0, 0, 0);
;       o[d0] = __builtin_amdgcn_mfma_f32_32x32x16_bf16(pa[2], AS_PK(l2, h2), o[d0], 0, 0, 0);
;       o[d0] = __builtin_amdgcn_mfma_f32_32x32x16_bf16(pa[3], AS_PK(l3, h3), o[d0], 0, 0, 0);
;     ...
;     }
.LBB0_1570:
	v_add_f32_e32 v6, v2, v3
	v_fmac_f32_e32 v6, v223, v0
	v_cvt_pk_bf16_f32 v2, v14, v15
	v_cvt_pk_bf16_f32 v3, v200, v201
	v_cvt_pk_bf16_f32 v4, v196, v197
	v_cvt_pk_bf16_f32 v5, v198, v199
	v_cvt_pk_bf16_f32 v192, v192, v193
	v_cvt_pk_bf16_f32 v193, v194, v195
	v_cvt_pk_bf16_f32 v194, v188, v189
	v_cvt_pk_bf16_f32 v195, v190, v191
	v_cvt_pk_bf16_f32 v184, v184, v185
	v_cvt_pk_bf16_f32 v185, v186, v187
	v_cvt_pk_bf16_f32 v186, v10, v11
	v_cvt_pk_bf16_f32 v187, v12, v202
	v_cvt_pk_bf16_f32 v10, v13, v7
	v_cvt_pk_bf16_f32 v11, v8, v9
	v_cvt_pk_bf16_f32 v12, v203, v224
	v_cvt_pk_bf16_f32 v13, v226, v227
	v_mov_b32_e32 v0, v209
	s_nop 0
	v_add_u32_e32 v7, v0, v211
	ds_read_b64_tr_b16 v[188:189], v7 offset:0
	v_add_u32_e32 v0, v0, v212
	ds_read_b64_tr_b16 v[190:191], v0 offset:0
	ds_read_b64_tr_b16 v[196:197], v7 offset:0x1000
	ds_read_b64_tr_b16 v[198:199], v0 offset:0x1000
	ds_read_b64_tr_b16 v[200:201], v7 offset:0x2000
	ds_read_b64_tr_b16 v[202:203], v0 offset:0x2000
	ds_read_b64_tr_b16 v[204:205], v7 offset:0x3000
	ds_read_b64_tr_b16 v[206:207], v0 offset:0x3000
	s_waitcnt lgkmcnt(0)
	s_nop 0
	v_mfma_f32_32x32x16_bf16 v[64:79], v[2:5], v[188:191], v[64:79]
	v_mov_b32_e32 v0, v209
	s_nop 0
	v_xor_b32_e32 v0, 64, v0
	v_add_u32_e32 v7, v0, v211
	ds_read_b64_tr_b16 v[188:189], v7 offset:0
	v_add_u32_e32 v0, v0, v212
	v_mfma_f32_32x32x16_bf16 v[64:79], v[192:195], v[196:199], v[64:79]
	ds_read_b64_tr_b16 v[190:191], v0 offset:0
	ds_read_b64_tr_b16 v[196:197], v7 offset:0x1000
	ds_read_b64_tr_b16 v[198:199], v0 offset:0x1000
	v_mfma_f32_32x32x16_bf16 v[64:79], v[184:187], v[200:203], v[64:79]
	ds_read_b64_tr_b16 v[200:201], v7 offset:0x2000
	ds_read_b64_tr_b16 v[202:203], v0 offset:0x2000
	v_mfma_f32_32x32x16_bf16 v[64:79], v[10:13], v[204:207], v[64:79]
	ds_read_b64_tr_b16 v[204:205], v7 offset:0x3000
	ds_read_b64_tr_b16 v[206:207], v0 offset:0x3000
	s_waitcnt lgkmcnt(0)
	v_mfma_f32_32x32x16_bf16 v[48:63], v[2:5], v[188:191], v[48:63]
	v_mov_b32_e32 v0, v209
	s_nop 0
	v_xor_b32_e32 v0, 0x80, v0
	v_add_u32_e32 v7, v0, v211
	ds_read_b64_tr_b16 v[188:189], v7 offset:0
	v_add_u32_e32 v0, v0, v212
	v_mfma_f32_32x32x16_bf16 v[48:63], v[192:195], v[196:199], v[48:63]
	ds_read_b64_tr_b16 v[190:191], v0 offset:0
	ds_read_b64_tr_b16 v[196:197], v7 offset:0x1000
	ds_read_b64_tr_b16 v[198:199], v0 offset:0x1000
	v_mfma_f32_32x32x16_bf16 v[48:63], v[184:187], v[200:203], v[48:63]
	ds_read_b64_tr_b16 v[200:201], v7 offset:0x2000
	ds_read_b64_tr_b16 v[202:203], v0 offset:0x2000
	v_mfma_f32_32x32x16_bf16 v[48:63], v[10:13], v[204:207], v[48:63]
	ds_read_b64_tr_b16 v[204:205], v7 offset:0x3000
	ds_read_b64_tr_b16 v[206:207], v0 offset:0x3000
	s_waitcnt lgkmcnt(0)
	v_mfma_f32_32x32x16_bf16 v[32:47], v[2:5], v[188:191], v[32:47]
	v_mov_b32_e32 v0, v209
	s_nop 0
	v_xor_b32_e32 v0, 0xc0, v0
	v_add_u32_e32 v7, v0, v211
	ds_read_b64_tr_b16 v[188:189], v7 offset:0
	v_add_u32_e32 v0, v0, v212
	v_mfma_f32_32x32x16_bf16 v[32:47], v[192:195], v[196:199], v[32:47]
	ds_read_b64_tr_b16 v[190:191], v0 offset:0
	ds_read_b64_tr_b16 v[196:197], v7 offset:0x1000
	ds_read_b64_tr_b16 v[198:199], v0 offset:0x1000
	v_mfma_f32_32x32x16_bf16 v[32:47], v[184:187], v[200:203], v[32:47]
	ds_read_b64_tr_b16 v[200:201], v7 offset:0x2000
	ds_read_b64_tr_b16 v[202:203], v0 offset:0x2000
	v_mfma_f32_32x32x16_bf16 v[32:47], v[10:13], v[204:207], v[32:47]
	ds_read_b64_tr_b16 v[204:205], v7 offset:0x3000
	ds_read_b64_tr_b16 v[206:207], v0 offset:0x3000
	s_waitcnt lgkmcnt(0)
	v_mfma_f32_32x32x16_bf16 v[16:31], v[2:5], v[188:191], v[16:31]
	s_cmp_gt_u32 s46, 63
	s_cbranch_scc1 .Lsa_cv_done
	s_cmp_gt_u32 s46, 62
	s_cbranch_scc1 .Lsa_cv_bf
	s_waitcnt vmcnt(10)
	v_cvt_pk_bf16_f32 v124, v100, v101
	v_cvt_pk_bf16_f32 v125, v102, v103
	v_cvt_pk_bf16_f32 v126, v96, v97
	v_cvt_pk_bf16_f32 v127, v98, v99
	v_cvt_pk_bf16_f32 v136, v112, v113
	v_cvt_pk_bf16_f32 v137, v114, v115
	v_cvt_pk_bf16_f32 v138, v108, v109
	v_cvt_pk_bf16_f32 v139, v110, v111
	v_cvt_pk_bf16_f32 v148, v140, v141
	v_cvt_pk_bf16_f32 v149, v142, v143
	v_cvt_pk_bf16_f32 v150, v120, v121
	v_cvt_pk_bf16_f32 v151, v122, v123
	v_cvt_pk_bf16_f32 v160, v152, v153
	v_cvt_pk_bf16_f32 v161, v154, v155
	v_cvt_pk_bf16_f32 v162, v132, v133
	v_cvt_pk_bf16_f32 v163, v134, v135
	s_branch .Lsa_cv_done
.Lsa_cv_bf:
	s_waitcnt vmcnt(5)
	v_mov_b64_e32 v[126:127], v[102:103]
	v_mov_b64_e32 v[138:139], v[114:115]
	v_mov_b64_e32 v[150:151], v[142:143]
	v_mov_b64_e32 v[162:163], v[154:155]
	v_mov_b64_e32 v[124:125], v[100:101]
	v_mov_b64_e32 v[136:137], v[112:113]
	v_mov_b64_e32 v[148:149], v[140:141]
	v_mov_b64_e32 v[160:161], v[152:153]
.Lsa_cv_done:
	s_add_u32 s14, s14, 0x20000
	s_addc_u32 s15, s15, 0
	s_add_u32 s18, s18, 0x4000
	s_addc_u32 s19, s19, 0
	s_add_i32 s46, s46, 1
	s_cmp_eq_u32 s14, 0x820000
	v_mfma_f32_32x32x16_bf16 v[16:31], v[192:195], v[196:199], v[16:31]
	v_mfma_f32_32x32x16_bf16 v[16:31], v[184:187], v[200:203], v[16:31]
	v_mfma_f32_32x32x16_bf16 v[16:31], v[10:13], v[204:207], v[16:31]
	s_cbranch_scc1 .LBB0_1573
	v_mov_b32_e32 v223, v6
	s_branch .LBB0_1551
